# attention epilogue: O stores widened from 64 two-byte stores to 32 dword stores per wave via DPP pairing of adjacent columns
# speedup vs baseline: 1.0062x; 1.0062x over previous
.LBB0_607:
	s_or_b64 exec, exec, s[0:1]
	s_waitcnt lgkmcnt(0)
	v_add_u32_e32 v80, s41, v96
	ds_read_b128 v[64:67], v80
	ds_read_b128 v[68:71], v80 offset:32
	ds_read_b128 v[72:75], v80 offset:64
	s_ashr_i32 s41, s40, 31
	s_lshl_b64 s[0:1], s[40:41], 12
	s_add_u32 s0, s38, s0
	s_addc_u32 s1, s39, s1
	s_mov_b32 vcc_lo, 0x55555555
	s_mov_b32 vcc_hi, 0x55555555
	v_lshlrev_b32_e32 v82, 14, v198
	v_lshl_add_u32 v82, v199, 1, v82
	v_mov_b32_e32 v83, 0
	v_mov_b32_e32 v81, 0xffe
	s_nop 1
	v_cndmask_b32_e32 v83, v81, v83, vcc
	v_add_u32_e32 v82, v82, v83
	s_waitcnt lgkmcnt(0)
	v_rcp_f32_e32 v64, v64
	v_rcp_f32_e32 v65, v65
	v_rcp_f32_e32 v66, v66
	v_rcp_f32_e32 v67, v67
	v_rcp_f32_e32 v68, v68
	v_rcp_f32_e32 v69, v69
	v_rcp_f32_e32 v70, v70
	v_rcp_f32_e32 v71, v71
	v_rcp_f32_e32 v72, v72
	v_rcp_f32_e32 v73, v73
	v_rcp_f32_e32 v74, v74
	v_rcp_f32_e32 v75, v75
	v_mov_b32_e32 v81, v82
	v_mul_f32_e32 v0, v0, v64
	v_mul_f32_e32 v1, v1, v65
	v_mul_f32_e32 v48, v48, v64
	v_mul_f32_e32 v49, v49, v65
	v_mov_b32_dpp v76, v0 quad_perm:[1,0,3,2] row_mask:0xf bank_mask:0xf
	v_mov_b32_dpp v77, v1 quad_perm:[1,0,3,2] row_mask:0xf bank_mask:0xf
	v_mov_b32_dpp v78, v48 quad_perm:[1,0,3,2] row_mask:0xf bank_mask:0xf
	v_mov_b32_dpp v79, v49 quad_perm:[1,0,3,2] row_mask:0xf bank_mask:0xf
	v_cndmask_b32_e32 v77, v77, v0, vcc
	v_cndmask_b32_e32 v76, v1, v76, vcc
	v_cndmask_b32_e32 v79, v79, v48, vcc
	v_cndmask_b32_e32 v78, v49, v78, vcc
	v_cvt_pk_bf16_f32 v76, v77, v76
	v_cvt_pk_bf16_f32 v78, v79, v78
	global_store_dword v81, v76, s[0:1]
	global_store_dword v81, v78, s[0:1] offset:64
	v_mul_f32_e32 v32, v32, v64
	v_mul_f32_e32 v33, v33, v65
	v_mul_f32_e32 v16, v16, v64
	v_mul_f32_e32 v17, v17, v65
	v_mov_b32_dpp v76, v32 quad_perm:[1,0,3,2] row_mask:0xf bank_mask:0xf
	v_mov_b32_dpp v77, v33 quad_perm:[1,0,3,2] row_mask:0xf bank_mask:0xf
	v_mov_b32_dpp v78, v16 quad_perm:[1,0,3,2] row_mask:0xf bank_mask:0xf
	v_mov_b32_dpp v79, v17 quad_perm:[1,0,3,2] row_mask:0xf bank_mask:0xf
	v_cndmask_b32_e32 v77, v77, v32, vcc
	v_cndmask_b32_e32 v76, v33, v76, vcc
	v_cndmask_b32_e32 v79, v79, v16, vcc
	v_cndmask_b32_e32 v78, v17, v78, vcc
	v_cvt_pk_bf16_f32 v76, v77, v76
	v_cvt_pk_bf16_f32 v78, v79, v78
	global_store_dword v81, v76, s[0:1] offset:128
	global_store_dword v81, v78, s[0:1] offset:192
	v_add_u32_e32 v81, 0x2000, v82
	v_mul_f32_e32 v2, v2, v66
	v_mul_f32_e32 v3, v3, v67
	v_mul_f32_e32 v50, v50, v66
	v_mul_f32_e32 v51, v51, v67
	v_mov_b32_dpp v76, v2 quad_perm:[1,0,3,2] row_mask:0xf bank_mask:0xf
	v_mov_b32_dpp v77, v3 quad_perm:[1,0,3,2] row_mask:0xf bank_mask:0xf
	v_mov_b32_dpp v78, v50 quad_perm:[1,0,3,2] row_mask:0xf bank_mask:0xf
	v_mov_b32_dpp v79, v51 quad_perm:[1,0,3,2] row_mask:0xf bank_mask:0xf
	v_cndmask_b32_e32 v77, v77, v2, vcc
	v_cndmask_b32_e32 v76, v3, v76, vcc
	v_cndmask_b32_e32 v79, v79, v50, vcc
	v_cndmask_b32_e32 v78, v51, v78, vcc
	v_cvt_pk_bf16_f32 v76, v77, v76
	v_cvt_pk_bf16_f32 v78, v79, v78
	global_store_dword v81, v76, s[0:1]
	global_store_dword v81, v78, s[0:1] offset:64
	v_mul_f32_e32 v34, v34, v66
	v_mul_f32_e32 v35, v35, v67
	v_mul_f32_e32 v18, v18, v66
	v_mul_f32_e32 v19, v19, v67
	v_mov_b32_dpp v76, v34 quad_perm:[1,0,3,2] row_mask:0xf bank_mask:0xf
	v_mov_b32_dpp v77, v35 quad_perm:[1,0,3,2] row_mask:0xf bank_mask:0xf
	v_mov_b32_dpp v78, v18 quad_perm:[1,0,3,2] row_mask:0xf bank_mask:0xf
	v_mov_b32_dpp v79, v19 quad_perm:[1,0,3,2] row_mask:0xf bank_mask:0xf
	v_cndmask_b32_e32 v77, v77, v34, vcc
	v_cndmask_b32_e32 v76, v35, v76, vcc
	v_cndmask_b32_e32 v79, v79, v18, vcc
	v_cndmask_b32_e32 v78, v19, v78, vcc
	v_cvt_pk_bf16_f32 v76, v77, v76
	v_cvt_pk_bf16_f32 v78, v79, v78
	global_store_dword v81, v76, s[0:1] offset:128
	global_store_dword v81, v78, s[0:1] offset:192
	ds_read_b128 v[0:3], v80 offset:96
	v_add_u32_e32 v81, 0x8000, v82
	v_mul_f32_e32 v4, v4, v68
	v_mul_f32_e32 v5, v5, v69
	v_mul_f32_e32 v52, v52, v68
	v_mul_f32_e32 v53, v53, v69
	v_mov_b32_dpp v76, v4 quad_perm:[1,0,3,2] row_mask:0xf bank_mask:0xf
	v_mov_b32_dpp v77, v5 quad_perm:[1,0,3,2] row_mask:0xf bank_mask:0xf
	v_mov_b32_dpp v78, v52 quad_perm:[1,0,3,2] row_mask:0xf bank_mask:0xf
	v_mov_b32_dpp v79, v53 quad_perm:[1,0,3,2] row_mask:0xf bank_mask:0xf
	v_cndmask_b32_e32 v77, v77, v4, vcc
	v_cndmask_b32_e32 v76, v5, v76, vcc
	v_cndmask_b32_e32 v79, v79, v52, vcc
	v_cndmask_b32_e32 v78, v53, v78, vcc
	v_cvt_pk_bf16_f32 v76, v77, v76
	v_cvt_pk_bf16_f32 v78, v79, v78
	global_store_dword v81, v76, s[0:1]
	global_store_dword v81, v78, s[0:1] offset:64
	v_mul_f32_e32 v36, v36, v68
	v_mul_f32_e32 v37, v37, v69
	v_mul_f32_e32 v20, v20, v68
	v_mul_f32_e32 v21, v21, v69
	v_mov_b32_dpp v76, v36 quad_perm:[1,0,3,2] row_mask:0xf bank_mask:0xf
	v_mov_b32_dpp v77, v37 quad_perm:[1,0,3,2] row_mask:0xf bank_mask:0xf
	v_mov_b32_dpp v78, v20 quad_perm:[1,0,3,2] row_mask:0xf bank_mask:0xf
	v_mov_b32_dpp v79, v21 quad_perm:[1,0,3,2] row_mask:0xf bank_mask:0xf
	v_cndmask_b32_e32 v77, v77, v36, vcc
	v_cndmask_b32_e32 v76, v37, v76, vcc
	v_cndmask_b32_e32 v79, v79, v20, vcc
	v_cndmask_b32_e32 v78, v21, v78, vcc
	v_cvt_pk_bf16_f32 v76, v77, v76
	v_cvt_pk_bf16_f32 v78, v79, v78
	global_store_dword v81, v76, s[0:1] offset:128
	global_store_dword v81, v78, s[0:1] offset:192
	v_add_u32_e32 v81, 0xa000, v82
	v_mul_f32_e32 v6, v6, v70
	v_mul_f32_e32 v7, v7, v71
	v_mul_f32_e32 v54, v54, v70
	v_mul_f32_e32 v55, v55, v71
	v_mov_b32_dpp v76, v6 quad_perm:[1,0,3,2] row_mask:0xf bank_mask:0xf
	v_mov_b32_dpp v77, v7 quad_perm:[1,0,3,2] row_mask:0xf bank_mask:0xf
	v_mov_b32_dpp v78, v54 quad_perm:[1,0,3,2] row_mask:0xf bank_mask:0xf
	v_mov_b32_dpp v79, v55 quad_perm:[1,0,3,2] row_mask:0xf bank_mask:0xf
	v_cndmask_b32_e32 v77, v77, v6, vcc
	v_cndmask_b32_e32 v76, v7, v76, vcc
	v_cndmask_b32_e32 v79, v79, v54, vcc
	v_cndmask_b32_e32 v78, v55, v78, vcc
	v_cvt_pk_bf16_f32 v76, v77, v76
	v_cvt_pk_bf16_f32 v78, v79, v78
	global_store_dword v81, v76, s[0:1]
	global_store_dword v81, v78, s[0:1] offset:64
	v_mul_f32_e32 v38, v38, v70
	v_mul_f32_e32 v39, v39, v71
	v_mul_f32_e32 v22, v22, v70
	v_mul_f32_e32 v23, v23, v71
	v_mov_b32_dpp v76, v38 quad_perm:[1,0,3,2] row_mask:0xf bank_mask:0xf
	v_mov_b32_dpp v77, v39 quad_perm:[1,0,3,2] row_mask:0xf bank_mask:0xf
	v_mov_b32_dpp v78, v22 quad_perm:[1,0,3,2] row_mask:0xf bank_mask:0xf
	v_mov_b32_dpp v79, v23 quad_perm:[1,0,3,2] row_mask:0xf bank_mask:0xf
	v_cndmask_b32_e32 v77, v77, v38, vcc
	v_cndmask_b32_e32 v76, v39, v76, vcc
	v_cndmask_b32_e32 v79, v79, v22, vcc
	v_cndmask_b32_e32 v78, v23, v78, vcc
	v_cvt_pk_bf16_f32 v76, v77, v76
	v_cvt_pk_bf16_f32 v78, v79, v78
	global_store_dword v81, v76, s[0:1] offset:128
	global_store_dword v81, v78, s[0:1] offset:192
	v_add_u32_e32 v81, 0x10000, v82
	v_mul_f32_e32 v8, v8, v72
	v_mul_f32_e32 v9, v9, v73
	v_mul_f32_e32 v56, v56, v72
	v_mul_f32_e32 v57, v57, v73
	v_mov_b32_dpp v76, v8 quad_perm:[1,0,3,2] row_mask:0xf bank_mask:0xf
	v_mov_b32_dpp v77, v9 quad_perm:[1,0,3,2] row_mask:0xf bank_mask:0xf
	v_mov_b32_dpp v78, v56 quad_perm:[1,0,3,2] row_mask:0xf bank_mask:0xf
	v_mov_b32_dpp v79, v57 quad_perm:[1,0,3,2] row_mask:0xf bank_mask:0xf
	v_cndmask_b32_e32 v77, v77, v8, vcc
	v_cndmask_b32_e32 v76, v9, v76, vcc
	v_cndmask_b32_e32 v79, v79, v56, vcc
	v_cndmask_b32_e32 v78, v57, v78, vcc
	v_cvt_pk_bf16_f32 v76, v77, v76
	v_cvt_pk_bf16_f32 v78, v79, v78
	global_store_dword v81, v76, s[0:1]
	global_store_dword v81, v78, s[0:1] offset:64
	v_mul_f32_e32 v40, v40, v72
	v_mul_f32_e32 v41, v41, v73
	v_mul_f32_e32 v24, v24, v72
	v_mul_f32_e32 v25, v25, v73
	v_mov_b32_dpp v76, v40 quad_perm:[1,0,3,2] row_mask:0xf bank_mask:0xf
	v_mov_b32_dpp v77, v41 quad_perm:[1,0,3,2] row_mask:0xf bank_mask:0xf
	v_mov_b32_dpp v78, v24 quad_perm:[1,0,3,2] row_mask:0xf bank_mask:0xf
	v_mov_b32_dpp v79, v25 quad_perm:[1,0,3,2] row_mask:0xf bank_mask:0xf
	v_cndmask_b32_e32 v77, v77, v40, vcc
	v_cndmask_b32_e32 v76, v41, v76, vcc
	v_cndmask_b32_e32 v79, v79, v24, vcc
	v_cndmask_b32_e32 v78, v25, v78, vcc
	v_cvt_pk_bf16_f32 v76, v77, v76
	v_cvt_pk_bf16_f32 v78, v79, v78
	global_store_dword v81, v76, s[0:1] offset:128
	global_store_dword v81, v78, s[0:1] offset:192
	v_add_u32_e32 v81, 0x12000, v82
	v_mul_f32_e32 v10, v10, v74
	v_mul_f32_e32 v11, v11, v75
	v_mul_f32_e32 v58, v58, v74
	v_mul_f32_e32 v59, v59, v75
	v_mov_b32_dpp v76, v10 quad_perm:[1,0,3,2] row_mask:0xf bank_mask:0xf
	v_mov_b32_dpp v77, v11 quad_perm:[1,0,3,2] row_mask:0xf bank_mask:0xf
	v_mov_b32_dpp v78, v58 quad_perm:[1,0,3,2] row_mask:0xf bank_mask:0xf
	v_mov_b32_dpp v79, v59 quad_perm:[1,0,3,2] row_mask:0xf bank_mask:0xf
	v_cndmask_b32_e32 v77, v77, v10, vcc
	v_cndmask_b32_e32 v76, v11, v76, vcc
	v_cndmask_b32_e32 v79, v79, v58, vcc
	v_cndmask_b32_e32 v78, v59, v78, vcc
	v_cvt_pk_bf16_f32 v76, v77, v76
	v_cvt_pk_bf16_f32 v78, v79, v78
	global_store_dword v81, v76, s[0:1]
	global_store_dword v81, v78, s[0:1] offset:64
	v_mul_f32_e32 v42, v42, v74
	v_mul_f32_e32 v43, v43, v75
	v_mul_f32_e32 v26, v26, v74
	v_mul_f32_e32 v27, v27, v75
	v_mov_b32_dpp v76, v42 quad_perm:[1,0,3,2] row_mask:0xf bank_mask:0xf
	v_mov_b32_dpp v77, v43 quad_perm:[1,0,3,2] row_mask:0xf bank_mask:0xf
	v_mov_b32_dpp v78, v26 quad_perm:[1,0,3,2] row_mask:0xf bank_mask:0xf
	v_mov_b32_dpp v79, v27 quad_perm:[1,0,3,2] row_mask:0xf bank_mask:0xf
	v_cndmask_b32_e32 v77, v77, v42, vcc
	v_cndmask_b32_e32 v76, v43, v76, vcc
	v_cndmask_b32_e32 v79, v79, v26, vcc
	v_cndmask_b32_e32 v78, v27, v78, vcc
	v_cvt_pk_bf16_f32 v76, v77, v76
	v_cvt_pk_bf16_f32 v78, v79, v78
	global_store_dword v81, v76, s[0:1] offset:128
	global_store_dword v81, v78, s[0:1] offset:192
	s_waitcnt lgkmcnt(0)
	v_rcp_f32_e32 v0, v0
	v_rcp_f32_e32 v1, v1
	v_rcp_f32_e32 v2, v2
	v_rcp_f32_e32 v3, v3
	s_nop 0
	v_add_u32_e32 v81, 0x18000, v82
	v_mul_f32_e32 v12, v12, v0
	v_mul_f32_e32 v13, v13, v1
	v_mul_f32_e32 v60, v60, v0
	v_mul_f32_e32 v61, v61, v1
	v_mov_b32_dpp v76, v12 quad_perm:[1,0,3,2] row_mask:0xf bank_mask:0xf
	v_mov_b32_dpp v77, v13 quad_perm:[1,0,3,2] row_mask:0xf bank_mask:0xf
	v_mov_b32_dpp v78, v60 quad_perm:[1,0,3,2] row_mask:0xf bank_mask:0xf
	v_mov_b32_dpp v79, v61 quad_perm:[1,0,3,2] row_mask:0xf bank_mask:0xf
	v_cndmask_b32_e32 v77, v77, v12, vcc
	v_cndmask_b32_e32 v76, v13, v76, vcc
	v_cndmask_b32_e32 v79, v79, v60, vcc
	v_cndmask_b32_e32 v78, v61, v78, vcc
	v_cvt_pk_bf16_f32 v76, v77, v76
	v_cvt_pk_bf16_f32 v78, v79, v78
	global_store_dword v81, v76, s[0:1]
	global_store_dword v81, v78, s[0:1] offset:64
	v_mul_f32_e32 v44, v44, v0
	v_mul_f32_e32 v45, v45, v1
	v_mul_f32_e32 v28, v28, v0
	v_mul_f32_e32 v29, v29, v1
	v_mov_b32_dpp v76, v44 quad_perm:[1,0,3,2] row_mask:0xf bank_mask:0xf
	v_mov_b32_dpp v77, v45 quad_perm:[1,0,3,2] row_mask:0xf bank_mask:0xf
	v_mov_b32_dpp v78, v28 quad_perm:[1,0,3,2] row_mask:0xf bank_mask:0xf
	v_mov_b32_dpp v79, v29 quad_perm:[1,0,3,2] row_mask:0xf bank_mask:0xf
	v_cndmask_b32_e32 v77, v77, v44, vcc
	v_cndmask_b32_e32 v76, v45, v76, vcc
	v_cndmask_b32_e32 v79, v79, v28, vcc
	v_cndmask_b32_e32 v78, v29, v78, vcc
	v_cvt_pk_bf16_f32 v76, v77, v76
	v_cvt_pk_bf16_f32 v78, v79, v78
	global_store_dword v81, v76, s[0:1] offset:128
	global_store_dword v81, v78, s[0:1] offset:192
	v_add_u32_e32 v81, 0x1a000, v82
	v_mul_f32_e32 v14, v14, v2
	v_mul_f32_e32 v15, v15, v3
	v_mul_f32_e32 v62, v62, v2
	v_mul_f32_e32 v63, v63, v3
	v_mov_b32_dpp v76, v14 quad_perm:[1,0,3,2] row_mask:0xf bank_mask:0xf
	v_mov_b32_dpp v77, v15 quad_perm:[1,0,3,2] row_mask:0xf bank_mask:0xf
	v_mov_b32_dpp v78, v62 quad_perm:[1,0,3,2] row_mask:0xf bank_mask:0xf
	v_mov_b32_dpp v79, v63 quad_perm:[1,0,3,2] row_mask:0xf bank_mask:0xf
	v_cndmask_b32_e32 v77, v77, v14, vcc
	v_cndmask_b32_e32 v76, v15, v76, vcc
	v_cndmask_b32_e32 v79, v79, v62, vcc
	v_cndmask_b32_e32 v78, v63, v78, vcc
	v_cvt_pk_bf16_f32 v76, v77, v76
	v_cvt_pk_bf16_f32 v78, v79, v78
	global_store_dword v81, v76, s[0:1]
	global_store_dword v81, v78, s[0:1] offset:64
	v_mul_f32_e32 v46, v46, v2
	v_mul_f32_e32 v47, v47, v3
	v_mul_f32_e32 v30, v30, v2
	v_mul_f32_e32 v31, v31, v3
	v_mov_b32_dpp v76, v46 quad_perm:[1,0,3,2] row_mask:0xf bank_mask:0xf
	v_mov_b32_dpp v77, v47 quad_perm:[1,0,3,2] row_mask:0xf bank_mask:0xf
	v_mov_b32_dpp v78, v30 quad_perm:[1,0,3,2] row_mask:0xf bank_mask:0xf
	v_mov_b32_dpp v79, v31 quad_perm:[1,0,3,2] row_mask:0xf bank_mask:0xf
	v_cndmask_b32_e32 v77, v77, v46, vcc
	v_cndmask_b32_e32 v76, v47, v76, vcc
	v_cndmask_b32_e32 v79, v79, v30, vcc
	v_cndmask_b32_e32 v78, v31, v78, vcc
	v_cvt_pk_bf16_f32 v76, v77, v76
	v_cvt_pk_bf16_f32 v78, v79, v78
	global_store_dword v81, v76, s[0:1] offset:128
	global_store_dword v81, v78, s[0:1] offset:192
	s_add_i32 s23, s23, s94
	s_add_i32 s3, s3, s94
	s_cmpk_gt_i32 s23, 0x3ff
	s_waitcnt vmcnt(63) expcnt(7) lgkmcnt(15)
	s_barrier
	s_cbranch_scc1 .LBB0_604
